# baseline (speedup 1.0000x reference)
;     __host__ __device__ bool next(int i, Unit& u) const {
;         const long L = (long)i * G + c; if (L >= nwg) return false;
;         int wgid = (int)L; { const int q = nwg / NXCD, r = nwg % NXCD, xcd = wgid % NXCD, off = wgid / NXCD; wgid = (xcd < r ? xcd * (q + 1) : r * (q + 1) + (xcd - r) * q) + off; }
;         const int nig = WGM * nN, gid = wgid / nig, fm = gid * WGM, gsz = (nM - fm) < WGM ? (nM - fm) : WGM;
;         u.pm = fm + ((wgid % nig) % gsz); u.pn = (wgid % nig) / gsz; return true;
; template <class Epi, class Sched, bool ALIGN_EPI = false, bool SP2 = false>
; __device__ __forceinline__ void gemm_phase(PG8_LAS unsigned char* lds, const Gemm g, const Sched& S, const Epi& E, const int tid) {
;     ...
;     if (!S.next(0, cur)) return;
.LBB0_499:
	s_andn2_b64 vcc, exec, s[4:5]
	s_mul_i32 s11, s88, 56
	s_cbranch_vccnz .LBB0_589
	v_readlane_b32 s0, v254, 17
	s_cmp_eq_u32 s0, 5
	s_mov_b32 s24, s90
	s_cselect_b64 s[0:1], -1, 0
	s_cmpk_gt_i32 s24, 0x162b
	v_readfirstlane_b32 s6, v213
	s_cbranch_scc1 .LBB0_524
	s_cmp_lt_u32 s24, 64
	s_cbranch_scc1 .Lmy_nd2
	s_bfe_u32 s2, s24, 0x20003
	s_cmp_eq_u32 s2, 0
	s_cbranch_scc1 .Lmy_nd2
.Lmy_dl2:
	s_sleep 52
	s_sub_u32 s2, s2, 1
	s_cmp_lg_u32 s2, 0
	s_cbranch_scc1 .Lmy_dl2
.Lmy_nd2:
	s_ashr_i32 s25, s24, 31
	s_lshr_b32 s2, s25, 29
	s_add_i32 s7, s24, s2
	s_and_b32 s2, s7, -8
	s_sub_i32 s5, s24, s2
	s_cmp_gt_i32 s5, 3
	s_mov_b64 s[2:3], -1
	s_cbranch_scc0 .LBB0_503
	s_mul_i32 s2, s5, 0x2c5
	s_add_i32 s4, s2, 4
	s_mov_b64 s[2:3], 0

;     __host__ __device__ bool next(int i, Unit& u) const {
;         const long L = (long)i * G + c; if (L >= nwg) return false;
;         int wgid = (int)L; { const int q = nwg / NXCD, r = nwg % NXCD, xcd = wgid % NXCD, off = wgid / NXCD; wgid = (xcd < r ? xcd * (q + 1) : r * (q + 1) + (xcd - r) * q) + off; }
;         const int nig = WGM * nN, gid = wgid / nig, fm = gid * WGM, gsz = (nM - fm) < WGM ? (nM - fm) : WGM;
;         u.pm = fm + ((wgid % nig) % gsz); u.pn = (wgid % nig) / gsz; return true;
; template <class Epi, class Sched, bool ALIGN_EPI = false, bool SP2 = false>
; __device__ __forceinline__ void gemm_phase(PG8_LAS unsigned char* lds, const Gemm g, const Sched& S, const Epi& E, const int tid) {
;     ...
;     if (!S.next(0, cur)) return;
.LBB0_597:
	s_mov_b32 s62, s90
	s_mul_i32 s20, s30, s61
	s_cmp_lt_i32 s62, s20
	s_cselect_b64 s[24:25], -1, 0
	s_cmp_ge_i32 s62, s20
	v_readfirstlane_b32 s21, v213
	s_cbranch_scc1 .LBB0_604
	s_cmp_lt_u32 s62, 64
	s_cbranch_scc1 .Lmy_nd3
	s_cmp_eq_u32 s20, 0x400
	s_cbranch_scc1 .Lmy_nd3
	s_bfe_u32 s10, s62, 0x20003
	s_cmp_eq_u32 s10, 0
	s_cbranch_scc1 .Lmy_nd3
.Lmy_dl3:
	s_sleep 52
	s_sub_u32 s10, s10, 1
	s_cmp_lg_u32 s10, 0
	s_cbranch_scc1 .Lmy_dl3
.Lmy_nd3:
	s_ashr_i32 s10, s62, 31
	s_lshr_b32 s10, s10, 29
	s_add_i32 s26, s62, s10
	s_lshr_b32 s35, s20, 3
	s_and_b32 s10, s26, -8
	s_and_b32 s36, s20, 4
	s_sub_i32 s31, s62, s10
	s_add_i32 s34, s35, 1
	s_cmp_ge_i32 s31, s36
	s_mov_b64 s[10:11], -1
	s_cbranch_scc0 .LBB0_600
	s_sub_i32 s11, s31, s36
	s_mul_i32 s10, s34, s36
	s_mul_i32 s11, s11, s35
	s_add_i32 s27, s11, s10
	s_mov_b64 s[10:11], 0
